# attention: K LDS tile chunks XOR-swizzled by row so the Q.K fragment ds_read_b128 are conflict-free
# speedup vs baseline: 1.0023x; 1.0006x over previous
.LBB0_1054:
	s_or_b64 exec, exec, s[4:5]
	v_mov_b32_e32 v0, s48
	s_waitcnt lgkmcnt(0)
	s_barrier
	ds_read_b32 v0, v0
	s_waitcnt lgkmcnt(0)
	v_cmp_lt_i32_e32 vcc, 63, v0
	v_readfirstlane_b32 s4, v0
	s_cbranch_vccnz .LBB0_1073
	s_mov_b64 s[82:83], s[0:1]
	v_mov_b32_e32 v100, v226
	s_load_dwordx2 s[50:51], s[82:83], 0x58
	s_and_b32 s5, s4, 1
	s_lshl_b32 s4, s4, 1
	s_and_b32 s4, s4, -4
	v_readlane_b32 s6, v254, 14
	s_sub_i32 s4, 0x7c, s4
	s_or_b32 s6, s5, s6
	v_readlane_b32 s5, v254, 13
	s_or_b32 s5, s4, s5
	s_waitcnt lgkmcnt(0)
	s_add_u32 s56, s50, 0xb400000
	s_addc_u32 s57, s51, 0
	s_bfe_u32 s9, s4, 0x50002
	v_readfirstlane_b32 s4, v100
	s_ashr_i32 s7, s4, 8
	s_lshl_b32 s22, s6, 1
	s_add_i32 s8, s7, s22
	v_and_b32_e32 v28, 15, v100
	s_lshl_b32 s5, s5, 4
	s_lshr_b32 s4, s4, 2
	s_lshl_b32 s8, s8, 7
	s_and_b32 s23, s5, 0xfffff800
	s_lshl_b32 s5, s9, 6
	v_and_or_b32 v127, s4, 48, v28
	s_add_i32 s4, s8, 0x800
	s_or_b32 s5, s5, s23
	s_ashr_i32 s4, s4, 7
	v_or_b32_e32 v96, s5, v127
	s_ashr_i32 s5, s4, 31
	s_lshl_b64 s[4:5], s[4:5], 21
	v_ashrrev_i32_e32 v18, 5, v100
	v_ashrrev_i32_e32 v97, 31, v96
	s_add_u32 s4, s56, s4
	v_add_u32_e32 v16, s23, v18
	v_bfe_u32 v29, v100, 4, 2
	s_addc_u32 s5, s57, s5
	v_lshlrev_b64 v[98:99], 8, v[96:97]
	v_ashrrev_i32_e32 v17, 31, v16
	v_lshl_add_u64 v[0:1], s[4:5], 0, v[98:99]
	v_lshlrev_b32_e32 v208, 4, v29
	v_and_b32_e32 v19, 16, v100
	v_lshlrev_b64 v[16:17], 8, v[16:17]
	s_lshl_b32 s4, s6, 22
	v_lshl_add_u64 v[12:13], v[0:1], 0, v[208:209]
	v_lshl_add_u64 v[16:17], s[56:57], 0, v[16:17]
	v_lshl_or_b32 v208, v19, 17, s4
	v_lshlrev_b32_e32 v19, 4, v100
	v_lshl_add_u64 v[16:17], v[16:17], 0, v[208:209]
	v_and_b32_e32 v208, 0xf0, v19
	v_lshl_add_u64 v[16:17], v[16:17], 0, v[208:209]
	v_ashrrev_i32_e32 v19, 3, v100
	s_ashr_i32 s4, s23, 6
	v_lshl_add_u64 v[102:103], v[16:17], 0, s[62:63]
	v_lshl_add_u32 v16, s6, 8, v19
	s_ashr_i32 s5, s4, 31
	v_add_u32_e32 v16, 0x400, v16
	s_lshl_b64 s[4:5], s[4:5], 18
	v_lshlrev_b32_e32 v21, 3, v100
	v_ashrrev_i32_e32 v17, 31, v16
	s_add_u32 s4, s50, s4
	v_and_b32_e32 v22, 56, v21
	s_addc_u32 s5, s51, s5
	v_lshlrev_b64 v[16:17], 7, v[16:17]
	v_lshl_add_u64 v[16:17], s[4:5], 0, v[16:17]
	v_lshlrev_b32_e32 v208, 1, v22
	v_lshl_add_u64 v[16:17], v[16:17], 0, v[208:209]
	v_lshl_add_u64 v[104:105], v[16:17], 0, s[64:65]
	v_mul_lo_u32 v16, v19, s49
	v_add_lshl_u32 v31, v16, v22, 1
	v_lshlrev_b32_e32 v16, 2, v100
	v_sub_u32_e64 v20, s9, 8 clamp
	v_and_b32_e32 v16, 64, v16
	v_add_u32_e32 v16, v16, v18
	v_lshlrev_b32_e32 v208, 18, v20
	v_mul_lo_u32 v56, v16, s28
	v_lshl_add_u64 v[16:17], v[104:105], 0, v[208:209]
	v_add_co_u32_e32 v18, vcc, s21, v16
	v_lshlrev_b32_e32 v208, 14, v20
	v_readfirstlane_b32 s31, v20
	v_and_b32_e32 v57, 0x78, v21
	v_addc_co_u32_e32 v19, vcc, 0, v17, vcc
	v_lshl_add_u64 v[20:21], v[102:103], 0, v[208:209]
	v_add_co_u32_e32 v22, vcc, s35, v20
	global_load_dwordx4 v[0:3], v[12:13], off
	global_load_dwordx4 v[4:7], v[12:13], off offset:64
	global_load_dwordx4 v[8:11], v[12:13], off offset:128
	s_nop 0
	global_load_dwordx4 v[12:15], v[12:13], off offset:192
	v_addc_co_u32_e32 v23, vcc, 0, v21, vcc
	v_add_co_u32_e32 v24, vcc, s20, v16
	s_mul_i32 s4, s7, 0x410
	s_nop 0
	v_addc_co_u32_e32 v25, vcc, 0, v17, vcc
	v_add_co_u32_e32 v26, vcc, s17, v20
	s_add_i32 s38, s4, 0
	s_nop 0
	v_addc_co_u32_e32 v27, vcc, 0, v21, vcc
	global_load_dwordx4 v[52:55], v[24:25], off
	global_load_dwordx4 v[48:51], v[26:27], off
	v_add_co_u32_e32 v24, vcc, s17, v16
	v_lshlrev_b32_e32 v30, 3, v29
	s_nop 0
	v_addc_co_u32_e32 v25, vcc, 0, v17, vcc
	v_add_co_u32_e32 v26, vcc, s34, v20
	s_or_b32 s84, s12, s22
	s_nop 0
	v_addc_co_u32_e32 v27, vcc, 0, v21, vcc
	global_load_dwordx4 v[44:47], v[24:25], off
	global_load_dwordx4 v[40:43], v[26:27], off
	global_load_dwordx4 v[64:67], v[18:19], off
	global_load_dwordx4 v[32:35], v[16:17], off
	global_load_dwordx4 v[60:63], v[22:23], off
	global_load_dwordx4 v[36:39], v[20:21], off
	v_and_b32_e32 v19, 64, v233
	v_xor_b32_e32 v18, 16, v233
	v_add_u32_e32 v19, 64, v19
	v_cmp_lt_i32_e64 s[4:5], v18, v19
	v_max_i32_e32 v20, 2, v100
	v_sub_u32_e32 v20, v20, v100
	v_cndmask_b32_e64 v18, v233, v18, s[4:5]
	v_lshlrev_b32_e32 v126, 2, v18
	v_xor_b32_e32 v18, 32, v233
	v_cmp_lt_i32_e64 s[4:5], v18, v19
	v_add_u32_e32 v20, 0x1ff, v20
	v_lshl_or_b32 v17, s7, 6, v28
	v_cndmask_b32_e64 v18, v233, v18, s[4:5]
	v_lshrrev_b32_e32 v21, 9, v20
	v_mul_lo_u32 v17, v17, s28
	v_lshlrev_b32_e32 v125, 2, v18
	v_lshl_or_b32 v18, s7, 7, v28
	v_add_u32_e32 v21, 1, v21
	v_add_lshl_u32 v16, v56, v57, 1
	v_cmp_lt_i32_e32 vcc, s24, v100
	v_add_lshl_u32 v17, v17, v30, 1
	v_mul_lo_u32 v18, v18, s16
	v_add_u32_e32 v19, 0, v30
	v_lshlrev_b32_e32 v208, 2, v29
	v_and_b32_e32 v129, 0xfffffe, v21
	v_mov_b32_e32 v135, 0
	s_mov_b32 s42, s76
	s_add_i32 s38, s38, 0x23000
	s_mov_b32 s85, s13
	v_not_b32_e32 v128, v208
	v_or_b32_e32 v124, 16, v208
	v_or_b32_e32 v123, 32, v208
	v_or_b32_e32 v122, 48, v208
	v_cmp_lt_u32_e64 s[4:5], s61, v20
	v_lshl_add_u32 v130, v129, 9, v100
	s_mov_b32 s86, s84
	s_mov_b32 s87, s13
	s_mov_b32 s88, s84
	s_mov_b32 s89, s13
	v_add_u32_e32 v101, 0x200, v100
	v_cmp_ne_u32_e64 s[6:7], v21, v129
	v_mov_b32_e32 v136, 0xf149f2ca
	v_add_u32_e32 v131, 0, v16
	v_add_u32_e32 v132, 0, v31
	s_xor_b64 s[90:91], vcc, -1
	v_add_u32_e32 v133, 0, v17
	v_add_u32_e32 v134, v19, v18
	v_and_b32_e32 v149, 15, v100
	v_add_u32_e32 v149, 4, v149
	v_bfe_u32 v149, v149, 3, 1
	v_bfe_u32 v150, v100, 4, 2
	v_xor_b32_e32 v151, v150, v149
	v_lshlrev_b32_e32 v151, 4, v151
	v_lshlrev_b32_e32 v150, 3, v150
	v_sub_u32_e32 v151, v151, v150
	v_add_u32_e32 v134, v134, v151
	v_and_b32_e32 v149, 7, v100
	v_lshlrev_b32_e32 v150, 4, v149
	v_sub_u32_e32 v132, v132, v150
	v_and_b32_e32 v150, 4, v149
	v_lshl_add_u32 v132, v150, 4, v132
	v_and_b32_e32 v150, 1, v149
	v_lshl_add_u32 v132, v150, 5, v132
	v_and_b32_e32 v150, 2, v149
	v_lshl_add_u32 v132, v150, 2, v132
	v_bfe_u32 v150, v100, 3, 4
	v_add_u32_e32 v150, 4, v150
	v_bfe_u32 v150, v150, 3, 1
	v_lshlrev_b32_e32 v150, 4, v150
	v_sub_u32_e32 v148, 16, v150
	v_add_u32_e32 v148, v148, v132
	v_add_u32_e32 v132, v132, v150
	s_mov_b32 s32, 0x11800
	v_bfe_u32 v149, v100, 5, 4
	v_add_u32_e32 v149, 4, v149
	v_bfe_u32 v149, v149, 3, 1
	v_and_b32_e32 v150, 1, v100
	v_lshlrev_b32_e32 v150, 5, v150
	v_sub_u32_e32 v150, 16, v150
	v_mul_i32_i24_e32 v149, v149, v150
	v_add_u32_e32 v131, v131, v149
	v_and_b32_e32 v149, 15, v100
	v_add_u32_e32 v149, 4, v149
	v_bfe_u32 v149, v149, 3, 1
	v_bfe_u32 v150, v100, 4, 1
	v_lshlrev_b32_e32 v150, 5, v150
	v_sub_u32_e32 v150, 16, v150
	v_mul_i32_i24_e32 v149, v149, v150
	v_add_u32_e32 v133, v133, v149
	s_mov_b32 s39, s31
	v_mov_b32_e32 v20, 0
	v_mov_b32_e32 v21, v135
	v_mov_b32_e32 v22, v135
	v_mov_b32_e32 v23, v135
	v_mov_b32_e32 v28, 0
	v_mov_b32_e32 v29, v135
	v_mov_b32_e32 v30, v135
	v_mov_b32_e32 v31, v135
	v_mov_b32_e32 v16, 0
	v_mov_b32_e32 v17, v135
	v_mov_b32_e32 v18, v135
	v_mov_b32_e32 v19, v135
	v_mov_b32_e32 v56, 0
	v_mov_b32_e32 v57, v135
	v_mov_b32_e32 v58, v135
	v_mov_b32_e32 v59, v135
	v_mov_b32_e32 v68, 0
	v_mov_b32_e32 v69, v135
	v_mov_b32_e32 v70, v135
	v_mov_b32_e32 v71, v135
	v_mov_b32_e32 v72, 0
	v_mov_b32_e32 v73, v135
	v_mov_b32_e32 v74, v135
	v_mov_b32_e32 v75, v135
	v_mov_b32_e32 v24, 0
	v_mov_b32_e32 v25, v135
	v_mov_b32_e32 v26, v135
	v_mov_b32_e32 v27, v135
	v_mov_b32_e32 v76, 0
	v_mov_b32_e32 v77, v135
	v_mov_b32_e32 v78, v135
	v_mov_b32_e32 v79, v135

.LBB0_1108:
	s_or_b64 exec, exec, s[4:5]
	v_mov_b32_e32 v0, s48
	s_waitcnt lgkmcnt(0)
	s_barrier
	ds_read_b32 v0, v0
	s_mov_b64 s[4:5], -1
	s_waitcnt lgkmcnt(0)
	v_cmp_lt_i32_e32 vcc, 63, v0
	v_readfirstlane_b32 s6, v0
	s_cbranch_vccnz .LBB0_1101
	s_mov_b64 s[82:83], s[0:1]
	v_mov_b32_e32 v100, v226
	s_load_dwordx2 s[56:57], s[82:83], 0x58
	s_lshl_b32 s5, s6, 1
	s_and_b32 s4, s6, 1
	s_and_b32 s5, s5, -4
	s_sub_i32 s5, 0x7c, s5
	s_or_b32 s6, s4, s38
	s_waitcnt lgkmcnt(0)
	s_add_u32 s80, s56, 0xb400000
	v_readfirstlane_b32 s4, v100
	s_addc_u32 s81, s57, 0
	s_ashr_i32 s7, s4, 8
	s_lshl_b32 s22, s6, 1
	s_bfe_u32 s9, s5, 0x50002
	s_add_i32 s8, s7, s22
	s_lshl_b32 s5, s5, 4
	v_and_b32_e32 v28, 15, v100
	s_or_b32 s5, s5, s39
	s_lshr_b32 s4, s4, 2
	s_lshl_b32 s8, s8, 7
	s_and_b32 s23, s5, 0xfffff800
	s_lshl_b32 s5, s9, 6
	v_and_or_b32 v127, s4, 48, v28
	s_add_i32 s4, s8, 0x800
	s_or_b32 s5, s5, s23
	s_ashr_i32 s4, s4, 7
	v_or_b32_e32 v96, s5, v127
	s_ashr_i32 s5, s4, 31
	s_lshl_b64 s[4:5], s[4:5], 21
	v_ashrrev_i32_e32 v18, 5, v100
	v_ashrrev_i32_e32 v97, 31, v96
	s_add_u32 s4, s80, s4
	v_add_u32_e32 v16, s23, v18
	v_bfe_u32 v29, v100, 4, 2
	s_addc_u32 s5, s81, s5
	v_lshlrev_b64 v[98:99], 8, v[96:97]
	v_ashrrev_i32_e32 v17, 31, v16
	v_lshl_add_u64 v[0:1], s[4:5], 0, v[98:99]
	v_lshlrev_b32_e32 v208, 4, v29
	v_and_b32_e32 v19, 16, v100
	v_lshlrev_b64 v[16:17], 8, v[16:17]
	s_lshl_b32 s4, s6, 22
	v_lshl_add_u64 v[12:13], v[0:1], 0, v[208:209]
	v_lshl_add_u64 v[16:17], s[80:81], 0, v[16:17]
	v_lshl_or_b32 v208, v19, 17, s4
	v_lshlrev_b32_e32 v19, 4, v100
	v_lshl_add_u64 v[16:17], v[16:17], 0, v[208:209]
	v_and_b32_e32 v208, 0xf0, v19
	v_lshl_add_u64 v[16:17], v[16:17], 0, v[208:209]
	v_ashrrev_i32_e32 v19, 3, v100
	s_ashr_i32 s4, s23, 6
	v_lshl_add_u64 v[102:103], v[16:17], 0, s[62:63]
	v_lshl_add_u32 v16, s6, 8, v19
	s_ashr_i32 s5, s4, 31
	v_add_u32_e32 v16, 0x400, v16
	s_lshl_b64 s[4:5], s[4:5], 18
	v_lshlrev_b32_e32 v21, 3, v100
	v_ashrrev_i32_e32 v17, 31, v16
	s_add_u32 s4, s56, s4
	v_and_b32_e32 v22, 56, v21
	s_addc_u32 s5, s57, s5
	v_lshlrev_b64 v[16:17], 7, v[16:17]
	v_lshl_add_u64 v[16:17], s[4:5], 0, v[16:17]
	v_lshlrev_b32_e32 v208, 1, v22
	v_lshl_add_u64 v[16:17], v[16:17], 0, v[208:209]
	v_lshl_add_u64 v[104:105], v[16:17], 0, s[64:65]
	v_mul_lo_u32 v16, v19, s49
	v_add_lshl_u32 v31, v16, v22, 1
	v_lshlrev_b32_e32 v16, 2, v100
	v_sub_u32_e64 v20, s9, 8 clamp
	v_and_b32_e32 v16, 64, v16
	v_add_u32_e32 v16, v16, v18
	v_lshlrev_b32_e32 v208, 18, v20
	v_mul_lo_u32 v56, v16, s28
	v_lshl_add_u64 v[16:17], v[104:105], 0, v[208:209]
	v_add_co_u32_e32 v18, vcc, s21, v16
	v_lshlrev_b32_e32 v208, 14, v20
	v_readfirstlane_b32 s40, v20
	v_and_b32_e32 v57, 0x78, v21
	v_addc_co_u32_e32 v19, vcc, 0, v17, vcc
	v_lshl_add_u64 v[20:21], v[102:103], 0, v[208:209]
	v_add_co_u32_e32 v22, vcc, s35, v20
	global_load_dwordx4 v[0:3], v[12:13], off
	global_load_dwordx4 v[4:7], v[12:13], off offset:64
	global_load_dwordx4 v[8:11], v[12:13], off offset:128
	s_nop 0
	global_load_dwordx4 v[12:15], v[12:13], off offset:192
	v_addc_co_u32_e32 v23, vcc, 0, v21, vcc
	v_add_co_u32_e32 v24, vcc, s20, v16
	s_mul_i32 s4, s7, 0x410
	s_nop 0
	v_addc_co_u32_e32 v25, vcc, 0, v17, vcc
	v_add_co_u32_e32 v26, vcc, s17, v20
	s_add_i32 s41, s4, 0
	s_nop 0
	v_addc_co_u32_e32 v27, vcc, 0, v21, vcc
	global_load_dwordx4 v[52:55], v[24:25], off
	global_load_dwordx4 v[48:51], v[26:27], off
	v_add_co_u32_e32 v24, vcc, s17, v16
	v_lshlrev_b32_e32 v30, 3, v29
	s_nop 0
	v_addc_co_u32_e32 v25, vcc, 0, v17, vcc
	v_add_co_u32_e32 v26, vcc, s34, v20
	s_or_b32 s84, s12, s22
	s_nop 0
	v_addc_co_u32_e32 v27, vcc, 0, v21, vcc
	global_load_dwordx4 v[44:47], v[24:25], off
	global_load_dwordx4 v[40:43], v[26:27], off
	global_load_dwordx4 v[64:67], v[18:19], off
	global_load_dwordx4 v[32:35], v[16:17], off
	global_load_dwordx4 v[60:63], v[22:23], off
	global_load_dwordx4 v[36:39], v[20:21], off
	v_and_b32_e32 v19, 64, v233
	v_xor_b32_e32 v18, 16, v233
	v_add_u32_e32 v19, 64, v19
	v_cmp_lt_i32_e64 s[4:5], v18, v19
	v_max_i32_e32 v20, 2, v100
	v_sub_u32_e32 v20, v20, v100
	v_cndmask_b32_e64 v18, v233, v18, s[4:5]
	v_lshlrev_b32_e32 v126, 2, v18
	v_xor_b32_e32 v18, 32, v233
	v_cmp_lt_i32_e64 s[4:5], v18, v19
	v_add_u32_e32 v20, 0x1ff, v20
	v_lshl_or_b32 v17, s7, 6, v28
	v_cndmask_b32_e64 v18, v233, v18, s[4:5]
	v_lshrrev_b32_e32 v21, 9, v20
	v_mul_lo_u32 v17, v17, s28
	v_lshlrev_b32_e32 v125, 2, v18
	v_lshl_or_b32 v18, s7, 7, v28
	v_add_u32_e32 v21, 1, v21
	v_add_lshl_u32 v16, v56, v57, 1
	v_cmp_lt_i32_e32 vcc, s24, v100
	v_add_lshl_u32 v17, v17, v30, 1
	v_mul_lo_u32 v18, v18, s16
	v_add_u32_e32 v19, 0, v30
	v_lshlrev_b32_e32 v208, 2, v29
	v_and_b32_e32 v129, 0xfffffe, v21
	v_mov_b32_e32 v135, 0
	s_mov_b32 s43, s76
	s_add_i32 s41, s41, 0x23000
	s_mov_b32 s85, s13
	v_not_b32_e32 v128, v208
	v_or_b32_e32 v124, 16, v208
	v_or_b32_e32 v123, 32, v208
	v_or_b32_e32 v122, 48, v208
	v_cmp_lt_u32_e64 s[4:5], s61, v20
	v_lshl_add_u32 v130, v129, 9, v100
	s_mov_b32 s86, s84
	s_mov_b32 s87, s13
	s_mov_b32 s88, s84
	s_mov_b32 s89, s13
	v_add_u32_e32 v101, 0x200, v100
	v_cmp_ne_u32_e64 s[6:7], v21, v129
	v_mov_b32_e32 v136, 0xf149f2ca
	v_add_u32_e32 v131, 0, v16
	v_add_u32_e32 v132, 0, v31
	s_xor_b64 s[90:91], vcc, -1
	v_add_u32_e32 v133, 0, v17
	v_add_u32_e32 v134, v19, v18
	v_and_b32_e32 v149, 15, v100
	v_add_u32_e32 v149, 4, v149
	v_bfe_u32 v149, v149, 3, 1
	v_bfe_u32 v150, v100, 4, 2
	v_xor_b32_e32 v151, v150, v149
	v_lshlrev_b32_e32 v151, 4, v151
	v_lshlrev_b32_e32 v150, 3, v150
	v_sub_u32_e32 v151, v151, v150
	v_add_u32_e32 v134, v134, v151
	v_and_b32_e32 v149, 7, v100
	v_lshlrev_b32_e32 v150, 4, v149
	v_sub_u32_e32 v132, v132, v150
	v_and_b32_e32 v150, 4, v149
	v_lshl_add_u32 v132, v150, 4, v132
	v_and_b32_e32 v150, 1, v149
	v_lshl_add_u32 v132, v150, 5, v132
	v_and_b32_e32 v150, 2, v149
	v_lshl_add_u32 v132, v150, 2, v132
	v_bfe_u32 v150, v100, 3, 4
	v_add_u32_e32 v150, 4, v150
	v_bfe_u32 v150, v150, 3, 1
	v_lshlrev_b32_e32 v150, 4, v150
	v_sub_u32_e32 v148, 16, v150
	v_add_u32_e32 v148, v148, v132
	v_add_u32_e32 v132, v132, v150
	s_mov_b32 s32, 0x11800
	v_bfe_u32 v149, v100, 5, 4
	v_add_u32_e32 v149, 4, v149
	v_bfe_u32 v149, v149, 3, 1
	v_and_b32_e32 v150, 1, v100
	v_lshlrev_b32_e32 v150, 5, v150
	v_sub_u32_e32 v150, 16, v150
	v_mul_i32_i24_e32 v149, v149, v150
	v_add_u32_e32 v131, v131, v149
	v_and_b32_e32 v149, 15, v100
	v_add_u32_e32 v149, 4, v149
	v_bfe_u32 v149, v149, 3, 1
	v_bfe_u32 v150, v100, 4, 1
	v_lshlrev_b32_e32 v150, 5, v150
	v_sub_u32_e32 v150, 16, v150
	v_mul_i32_i24_e32 v149, v149, v150
	v_add_u32_e32 v133, v133, v149
	s_mov_b32 s42, s40
	v_mov_b32_e32 v20, 0
	v_mov_b32_e32 v21, v135
	v_mov_b32_e32 v22, v135
	v_mov_b32_e32 v23, v135
	v_mov_b32_e32 v28, 0
	v_mov_b32_e32 v29, v135
	v_mov_b32_e32 v30, v135
	v_mov_b32_e32 v31, v135
	v_mov_b32_e32 v16, 0
	v_mov_b32_e32 v17, v135
	v_mov_b32_e32 v18, v135
	v_mov_b32_e32 v19, v135
	v_mov_b32_e32 v56, 0
	v_mov_b32_e32 v57, v135
	v_mov_b32_e32 v58, v135
	v_mov_b32_e32 v59, v135
	v_mov_b32_e32 v68, 0
	v_mov_b32_e32 v69, v135
	v_mov_b32_e32 v70, v135
	v_mov_b32_e32 v71, v135
	v_mov_b32_e32 v72, 0
	v_mov_b32_e32 v73, v135
	v_mov_b32_e32 v74, v135
	v_mov_b32_e32 v75, v135
	v_mov_b32_e32 v24, 0
	v_mov_b32_e32 v25, v135
	v_mov_b32_e32 v26, v135
	v_mov_b32_e32 v27, v135
	v_mov_b32_e32 v76, 0
	v_mov_b32_e32 v77, v135
	v_mov_b32_e32 v78, v135
	v_mov_b32_e32 v79, v135
